# CMP GEMM split-K across workgroup pairs (all 256 WGs active; K-half 1 hands raw f32 accumulators to its partner through d_ws + flag)
# baseline (speedup 1.0000x reference)
.LBB0_849:
	s_mov_b32 s100, s33
	s_lshr_b32 s101, s33, 7
	s_and_b32 s33, s33, 0x7f
	s_cmp_lt_i32 s46, 9
	s_cselect_b64 s[0:1], -1, 0
	s_and_b64 s[4:5], s[0:1], s[2:3]
	s_andn2_b64 vcc, exec, s[4:5]
	s_cbranch_vccnz .LBB0_1134
	v_mov_b32_e32 v8, v188
	s_cmpk_lt_i32 s33, 0x80
	s_cselect_b64 s[0:1], -1, 0
	s_cmpk_gt_i32 s33, 0x7f
	v_readfirstlane_b32 s38, v8
	s_cbranch_scc1 .LBB0_856
	s_ashr_i32 s2, s33, 31
	s_lshr_b32 s2, s2, 29
	s_add_i32 s6, s33, s2
	s_and_b32 s2, s6, -8
	s_sub_i32 s7, s33, s2
	s_cmp_gt_i32 s7, -1
	s_cbranch_scc0 .LBB0_853
	s_lshl_b32 s8, s7, 4
	s_cbranch_execz .LBB0_854
	s_branch .LBB0_855

.LBB0_856:
	s_andn2_b64 vcc, exec, s[0:1]
	s_cbranch_vccnz .LBB0_1134
	v_bfe_i32 v2, v8, 27, 1
	v_lshlrev_b32_e32 v0, 4, v8
	v_lshrrev_b32_e32 v2, 22, v2
	v_add_u32_e32 v2, v0, v2
	v_and_b32_e32 v2, 0xfffffc00, v2
	v_sub_u32_e32 v2, v0, v2
	s_waitcnt lgkmcnt(0)
	v_ashrrev_i32_e32 v1, 31, v8
	v_lshrrev_b32_e32 v3, 4, v2
	v_lshrrev_b32_e32 v1, 26, v1
	v_bitop3_b32 v2, v3, v2, 32 bitop3:0x6c
	v_add_u32_e32 v1, v8, v1
	v_ashrrev_i32_e32 v4, 31, v2
	v_ashrrev_i32_e32 v1, 6, v1
	v_lshrrev_b32_e32 v4, 26, v4
	v_lshlrev_b32_e32 v3, 3, v1
	v_add_u32_e32 v4, v2, v4
	v_lshlrev_b32_e32 v1, 5, v1
	v_and_b32_e32 v3, -16, v3
	v_ashrrev_i32_e32 v5, 6, v4
	v_and_b32_e32 v9, 32, v1
	v_and_b32_e32 v1, 0xc0, v4
	v_add_u32_e32 v3, v5, v3
	v_sub_u32_e32 v1, v2, v1
	v_mov_b32_e32 v2, 1
	v_and_b32_e32 v5, 3, v5
	s_mov_b32 s1, 0xfffe0
	v_ashrrev_i16_sdwa v1, v2, sext(v1) dst_sel:DWORD dst_unused:UNUSED_PAD src0_sel:DWORD src1_sel:BYTE_0
	v_lshlrev_b32_e32 v4, 1, v3
	v_lshrrev_b32_e32 v6, 2, v3
	v_and_or_b32 v5, v3, s1, v5
	s_movk_i32 s2, 0x6000
	v_lshlrev_b32_e32 v3, 6, v3
	v_bfe_i32 v10, v1, 0, 16
	v_mul_lo_u32 v11, v6, s2
	v_and_b32_e32 v12, 0xc0, v3
	v_add_u32_e32 v1, v9, v10
	v_and_b32_e32 v4, 24, v4
	v_and_b32_e32 v7, 4, v6
	v_or_b32_e32 v3, v11, v12
	v_or3_b32 v4, v5, v7, v4
	v_add_lshl_u32 v72, v3, v1, 1
	v_lshlrev_b32_e32 v1, 1, v1
	v_add_u32_e32 v0, 0x2000, v0
	v_lshl_add_u32 v74, v4, 12, v1
	v_ashrrev_i32_e32 v1, 31, v0
	v_lshrrev_b32_e32 v1, 22, v1
	v_add_u32_e32 v1, v0, v1
	v_ashrrev_i32_e32 v1, 10, v1
	v_mul_i32_i24_e32 v3, 0x400, v1
	v_sub_u32_e32 v0, v0, v3
	v_lshrrev_b32_e32 v3, 4, v0
	v_bitop3_b32 v0, v3, v0, 32 bitop3:0x6c
	v_ashrrev_i32_e32 v4, 31, v0
	v_lshrrev_b32_e32 v4, 26, v4
	v_lshlrev_b32_e32 v3, 3, v1
	v_add_u32_e32 v4, v0, v4
	v_lshlrev_b32_e32 v1, 5, v1
	v_and_b32_e32 v3, -16, v3
	v_ashrrev_i32_e32 v5, 6, v4
	v_and_b32_e32 v13, 32, v1
	v_and_b32_e32 v1, 0xc0, v4
	s_add_u32 s39, s44, 0x3080000
	v_add_u32_e32 v3, v5, v3
	v_sub_u32_e32 v0, v0, v1
	s_addc_u32 s40, s45, 0
	s_lshl_b32 s99, s101, 11
	s_add_u32 s39, s39, s99
	s_addc_u32 s40, s40, 0
	s_ashr_i32 s0, s38, 6
	v_ashrrev_i16_sdwa v0, v2, sext(v0) dst_sel:DWORD dst_unused:UNUSED_PAD src0_sel:DWORD src1_sel:BYTE_0
	v_lshrrev_b32_e32 v2, 2, v3
	v_and_b32_e32 v5, 3, v5
	s_ashr_i32 s31, s30, 31
	v_and_or_b32 v5, v3, s1, v5
	v_mul_lo_u32 v15, v2, s2
	s_ashr_i32 s1, s38, 8
	s_lshl_b32 s41, s0, 10
	s_lshl_b64 s[2:3], s[30:31], 9
	s_lshl_b64 s[6:7], s[30:31], 20
	s_add_u32 s36, s39, s6
	s_addc_u32 s37, s40, s7
	s_add_i32 s42, s41, 0
	s_add_i32 m0, s42, 0x10000
	v_and_b32_e32 v4, 4, v2
	v_lshlrev_b32_e32 v2, 6, v3
	s_mul_i32 s9, s70, 0x300000
	global_load_lds_dwordx4 v74, s[36:37]
	s_add_i32 m0, s42, 0x12000
	v_bfe_i32 v14, v0, 0, 16
	v_lshlrev_b32_e32 v1, 1, v3
	s_waitcnt vmcnt(0)
	v_and_b32_e32 v16, 0xc0, v2
	s_mul_hi_i32 s8, s70, 0x300000
	s_add_u32 s6, s24, s9
	v_add_u32_e32 v0, v13, v14
	v_and_b32_e32 v1, 24, v1
	v_or_b32_e32 v2, v15, v16
	s_addc_u32 s7, s25, s8
	v_or3_b32 v1, v5, v4, v1
	v_add_lshl_u32 v76, v2, v0, 1
	v_lshlrev_b32_e32 v0, 1, v0
	s_add_u32 s34, s6, s2
	v_lshl_add_u32 v78, v1, 12, v0
	s_addc_u32 s35, s7, s3
	s_mul_i32 s99, s101, 0xc000
	s_add_u32 s34, s34, s99
	s_addc_u32 s35, s35, 0
	s_add_i32 s43, s42, 0x2000
	global_load_lds_dwordx4 v78, s[36:37]
	s_mov_b32 m0, s42
	s_add_u32 s2, s36, 0x80000
	global_load_lds_dwordx4 v72, s[34:35]
	s_mov_b32 m0, s43
	s_addc_u32 s3, s37, 0
	s_add_i32 s44, s42, 0x14000
	global_load_lds_dwordx4 v76, s[34:35]
	s_mov_b32 m0, s44
	s_add_i32 s45, s42, 0x16000
	global_load_lds_dwordx4 v74, s[2:3]
	s_mov_b32 m0, s45
	v_mov_b32_e32 v81, 0
	global_load_lds_dwordx4 v78, s[2:3]
	s_add_u32 s2, s34, 0x180000
	s_addc_u32 s3, s35, 0
	s_add_i32 s46, s42, 0x4000
	s_mov_b32 m0, s46
	s_add_i32 s47, s42, 0x6000
	global_load_lds_dwordx4 v72, s[2:3]
	s_mov_b32 m0, s47
	v_mov_b32_e32 v75, v81
	global_load_lds_dwordx4 v76, s[2:3]
	v_mov_b32_e32 v79, v81
	v_mov_b32_e32 v73, v81
	v_mov_b32_e32 v77, v81
	s_mov_b32 s48, 0
	s_mov_b32 s49, 0x10000
	v_lshl_add_u64 v[6:7], s[36:37], 0, v[74:75]
	v_lshl_add_u64 v[4:5], s[36:37], 0, v[78:79]
	s_mov_b32 s50, 0x12000
	v_lshl_add_u64 v[2:3], s[34:35], 0, v[72:73]
	v_lshl_add_u64 v[0:1], s[34:35], 0, v[76:77]
	s_cmp_lg_u32 s1, 1
	s_mov_b32 s51, 0x14000
	s_cbranch_scc1 .LBB0_859
	s_barrier

.LBB0_870:
	v_add_u32_e32 v80, s60, v94
	ds_read_b128 v[8:11], v80
	ds_read_b128 v[16:19], v80 offset:1024
	ds_read_b128 v[98:101], v80 offset:2048
	ds_read_b128 v[102:105], v80 offset:3072
	s_and_b64 s[0:1], exec, s[0:1]
	s_cselect_b32 s1, s21, s78
	s_cselect_b32 s0, s31, s71
	v_lshl_add_u64 v[138:139], s[34:35], 0, v[86:87]
	s_add_i32 m0, s42, 0xc000
	ds_read_b128 v[106:109], v95
	ds_read_b128 v[110:113], v95 offset:1024
	ds_read_b128 v[114:117], v95 offset:2048
	ds_read_b128 v[118:121], v95 offset:3072
	ds_read_b128 v[122:125], v95 offset:4096
	ds_read_b128 v[126:129], v95 offset:5120
	ds_read_b128 v[130:133], v95 offset:6144
	ds_read_b128 v[134:137], v95 offset:7168
	global_load_lds_dwordx4 v[138:139], off
	v_lshl_add_u64 v[138:139], s[34:35], 0, v[88:89]
	s_add_i32 m0, s42, 0xe000
	s_nop 0
	global_load_lds_dwordx4 v[138:139], off
	s_waitcnt lgkmcnt(8)
	s_barrier
	s_waitcnt lgkmcnt(0)
	s_setprio 1
	s_waitcnt lgkmcnt(0)
	v_mfma_f32_16x16x32_bf16 v[68:71], v[8:11], v[106:109], v[68:71]
	v_mfma_f32_16x16x32_bf16 v[64:67], v[98:101], v[106:109], v[64:67]
	v_mfma_f32_16x16x32_bf16 v[60:63], v[8:11], v[114:117], v[60:63]
	v_mfma_f32_16x16x32_bf16 v[56:59], v[98:101], v[114:117], v[56:59]
	v_mfma_f32_16x16x32_bf16 v[52:55], v[8:11], v[122:125], v[52:55]
	v_mfma_f32_16x16x32_bf16 v[48:51], v[98:101], v[122:125], v[48:51]
	v_mfma_f32_16x16x32_bf16 v[44:47], v[8:11], v[130:133], v[44:47]
	v_mfma_f32_16x16x32_bf16 v[40:43], v[98:101], v[130:133], v[40:43]
	v_mfma_f32_16x16x32_bf16 v[68:71], v[16:19], v[110:113], v[68:71]
	v_mfma_f32_16x16x32_bf16 v[64:67], v[102:105], v[110:113], v[64:67]
	v_mfma_f32_16x16x32_bf16 v[60:63], v[16:19], v[118:121], v[60:63]
	v_mfma_f32_16x16x32_bf16 v[56:59], v[102:105], v[118:121], v[56:59]
	v_mfma_f32_16x16x32_bf16 v[52:55], v[16:19], v[126:129], v[52:55]
	v_mfma_f32_16x16x32_bf16 v[48:51], v[102:105], v[126:129], v[48:51]
	v_mfma_f32_16x16x32_bf16 v[44:47], v[16:19], v[134:137], v[44:47]
	v_mfma_f32_16x16x32_bf16 v[40:43], v[102:105], v[134:137], v[40:43]
	s_setprio 0
	s_barrier
	s_add_i32 s80, s60, s41
	v_lshl_add_u64 v[138:139], s[0:1], 0, v[74:75]
	s_mov_b32 m0, s80
	v_lshl_add_u64 v[140:141], s[0:1], 0, v[78:79]
	global_load_lds_dwordx4 v[138:139], off
	s_add_i32 m0, s80, 0x2000
	s_nop 0
	global_load_lds_dwordx4 v[140:141], off
	s_barrier
	s_waitcnt lgkmcnt(0)
	s_setprio 1
	s_setprio 0
	s_mov_b32 m0, s42
	v_lshl_add_u64 v[142:143], s[36:37], 0, v[72:73]
	s_barrier
	ds_read_b128 v[106:109], v95 offset:16384
	ds_read_b128 v[110:113], v95 offset:17408
	ds_read_b128 v[114:117], v95 offset:18432
	ds_read_b128 v[118:121], v95 offset:19456
	ds_read_b128 v[122:125], v95 offset:20480
	ds_read_b128 v[126:129], v95 offset:21504
	ds_read_b128 v[130:133], v95 offset:22528
	ds_read_b128 v[134:137], v95 offset:23552
	global_load_lds_dwordx4 v[142:143], off
	v_lshl_add_u64 v[144:145], s[36:37], 0, v[76:77]
	s_mov_b32 m0, s43
	s_nop 0
	global_load_lds_dwordx4 v[144:145], off
	s_barrier
	s_waitcnt lgkmcnt(0)
	s_setprio 1
	s_waitcnt lgkmcnt(0)
	v_mfma_f32_16x16x32_bf16 v[36:39], v[8:11], v[106:109], v[36:39]
	v_mfma_f32_16x16x32_bf16 v[32:35], v[98:101], v[106:109], v[32:35]
	v_mfma_f32_16x16x32_bf16 v[28:31], v[8:11], v[114:117], v[28:31]
	v_mfma_f32_16x16x32_bf16 v[24:27], v[98:101], v[114:117], v[24:27]
	v_mfma_f32_16x16x32_bf16 v[20:23], v[8:11], v[122:125], v[20:23]
	v_mfma_f32_16x16x32_bf16 v[12:15], v[98:101], v[122:125], v[12:15]
	v_mfma_f32_16x16x32_bf16 v[4:7], v[8:11], v[130:133], v[4:7]
	v_mfma_f32_16x16x32_bf16 v[0:3], v[98:101], v[130:133], v[0:3]
	v_mfma_f32_16x16x32_bf16 v[36:39], v[16:19], v[110:113], v[36:39]
	v_mfma_f32_16x16x32_bf16 v[32:35], v[102:105], v[110:113], v[32:35]
	v_mfma_f32_16x16x32_bf16 v[28:31], v[16:19], v[118:121], v[28:31]
	v_mfma_f32_16x16x32_bf16 v[24:27], v[102:105], v[118:121], v[24:27]
	v_mfma_f32_16x16x32_bf16 v[20:23], v[16:19], v[126:129], v[20:23]
	v_mfma_f32_16x16x32_bf16 v[12:15], v[102:105], v[126:129], v[12:15]
	v_mfma_f32_16x16x32_bf16 v[4:7], v[16:19], v[134:137], v[4:7]
	v_mfma_f32_16x16x32_bf16 v[0:3], v[102:105], v[134:137], v[0:3]
	s_setprio 0
	s_barrier
	s_add_u32 s80, s0, 0x80000
	s_addc_u32 s81, s1, 0
	s_mov_b32 m0, s44
	v_lshl_add_u64 v[8:9], s[80:81], 0, v[74:75]
	global_load_lds_dwordx4 v[8:9], off
	v_lshl_add_u64 v[8:9], s[80:81], 0, v[78:79]
	s_mov_b32 m0, s45
	s_nop 0
	global_load_lds_dwordx4 v[8:9], off
	s_waitcnt vmcnt(6)
	s_barrier
	s_setprio 1
	s_setprio 0
	s_add_i32 s80, 0, 0x18000
	v_add_u32_e32 v80, s80, v94
	s_barrier
	ds_read_b128 v[8:11], v80
	ds_read_b128 v[16:19], v80 offset:1024
	ds_read_b128 v[98:101], v80 offset:2048
	ds_read_b128 v[102:105], v80 offset:3072
	s_add_u32 s36, s36, 0x180000
	s_addc_u32 s37, s37, 0
	s_mov_b32 m0, s46
	v_lshl_add_u64 v[146:147], s[36:37], 0, v[72:73]
	ds_read_b128 v[106:109], v95 offset:32768
	ds_read_b128 v[110:113], v95 offset:33792
	ds_read_b128 v[114:117], v95 offset:34816
	ds_read_b128 v[118:121], v95 offset:35840
	ds_read_b128 v[122:125], v95 offset:36864
	ds_read_b128 v[126:129], v95 offset:37888
	ds_read_b128 v[130:133], v95 offset:38912
	ds_read_b128 v[134:137], v95 offset:39936
	global_load_lds_dwordx4 v[146:147], off
	v_lshl_add_u64 v[146:147], s[36:37], 0, v[76:77]
	s_mov_b32 m0, s47
	s_nop 0
	global_load_lds_dwordx4 v[146:147], off
	s_waitcnt lgkmcnt(8)
	s_barrier
	s_waitcnt lgkmcnt(0)
	s_setprio 1
	s_waitcnt lgkmcnt(0)
	v_mfma_f32_16x16x32_bf16 v[68:71], v[8:11], v[106:109], v[68:71]
	v_mfma_f32_16x16x32_bf16 v[64:67], v[98:101], v[106:109], v[64:67]
	v_mfma_f32_16x16x32_bf16 v[60:63], v[8:11], v[114:117], v[60:63]
	v_mfma_f32_16x16x32_bf16 v[56:59], v[98:101], v[114:117], v[56:59]
	v_mfma_f32_16x16x32_bf16 v[52:55], v[8:11], v[122:125], v[52:55]
	v_mfma_f32_16x16x32_bf16 v[48:51], v[98:101], v[122:125], v[48:51]
	v_mfma_f32_16x16x32_bf16 v[44:47], v[8:11], v[130:133], v[44:47]
	v_mfma_f32_16x16x32_bf16 v[40:43], v[98:101], v[130:133], v[40:43]
	v_mfma_f32_16x16x32_bf16 v[68:71], v[16:19], v[110:113], v[68:71]
	v_mfma_f32_16x16x32_bf16 v[64:67], v[102:105], v[110:113], v[64:67]
	v_mfma_f32_16x16x32_bf16 v[60:63], v[16:19], v[118:121], v[60:63]
	v_mfma_f32_16x16x32_bf16 v[56:59], v[102:105], v[118:121], v[56:59]
	v_mfma_f32_16x16x32_bf16 v[52:55], v[16:19], v[126:129], v[52:55]
	v_mfma_f32_16x16x32_bf16 v[48:51], v[102:105], v[126:129], v[48:51]
	v_mfma_f32_16x16x32_bf16 v[44:47], v[16:19], v[134:137], v[44:47]
	v_mfma_f32_16x16x32_bf16 v[40:43], v[102:105], v[134:137], v[40:43]
	s_setprio 0
	s_barrier
	s_add_i32 s36, s80, s41
	v_lshl_add_u64 v[106:107], v[138:139], 0, s[6:7]
	s_mov_b32 m0, s36
	s_nop 0
	global_load_lds_dwordx4 v[106:107], off
	v_lshl_add_u64 v[106:107], v[140:141], 0, s[6:7]
	s_add_i32 m0, s36, 0x2000
	s_nop 0
	global_load_lds_dwordx4 v[106:107], off
	s_barrier
	s_waitcnt lgkmcnt(0)
	s_setprio 1
	s_setprio 0
	s_mov_b32 m0, s54
	v_lshl_add_u64 v[138:139], v[142:143], 0, s[8:9]
	s_barrier
	ds_read_b128 v[106:109], v95 offset:49152
	ds_read_b128 v[110:113], v95 offset:50176
	ds_read_b128 v[114:117], v95 offset:51200
	ds_read_b128 v[118:121], v95 offset:52224
	ds_read_b128 v[122:125], v95 offset:53248
	ds_read_b128 v[126:129], v95 offset:54272
	ds_read_b128 v[130:133], v95 offset:55296
	ds_read_b128 v[134:137], v95 offset:56320
	global_load_lds_dwordx4 v[138:139], off
	v_lshl_add_u64 v[138:139], v[144:145], 0, s[8:9]
	s_mov_b32 m0, s55
	s_nop 0
	global_load_lds_dwordx4 v[138:139], off
	s_barrier
	s_waitcnt lgkmcnt(0)
	s_setprio 1
	s_waitcnt lgkmcnt(0)
	v_mfma_f32_16x16x32_bf16 v[36:39], v[8:11], v[106:109], v[36:39]
	v_mfma_f32_16x16x32_bf16 v[32:35], v[98:101], v[106:109], v[32:35]
	v_mfma_f32_16x16x32_bf16 v[28:31], v[8:11], v[114:117], v[28:31]
	v_mfma_f32_16x16x32_bf16 v[24:27], v[98:101], v[114:117], v[24:27]
	v_mfma_f32_16x16x32_bf16 v[20:23], v[8:11], v[122:125], v[20:23]
	v_mfma_f32_16x16x32_bf16 v[12:15], v[98:101], v[122:125], v[12:15]
	v_mfma_f32_16x16x32_bf16 v[4:7], v[8:11], v[130:133], v[4:7]
	v_mfma_f32_16x16x32_bf16 v[0:3], v[98:101], v[130:133], v[0:3]
	v_mfma_f32_16x16x32_bf16 v[36:39], v[16:19], v[110:113], v[36:39]
	v_mfma_f32_16x16x32_bf16 v[32:35], v[102:105], v[110:113], v[32:35]
	v_mfma_f32_16x16x32_bf16 v[28:31], v[16:19], v[118:121], v[28:31]
	v_mfma_f32_16x16x32_bf16 v[24:27], v[102:105], v[118:121], v[24:27]
	v_mfma_f32_16x16x32_bf16 v[20:23], v[16:19], v[126:129], v[20:23]
	v_mfma_f32_16x16x32_bf16 v[12:15], v[102:105], v[126:129], v[12:15]
	v_mfma_f32_16x16x32_bf16 v[4:7], v[16:19], v[134:137], v[4:7]
	v_mfma_f32_16x16x32_bf16 v[0:3], v[102:105], v[134:137], v[0:3]
	s_setprio 0
	s_barrier
	s_add_u32 s0, s0, 0x80080
	s_addc_u32 s1, s1, 0
	s_mov_b32 m0, s56
	v_lshl_add_u64 v[8:9], s[0:1], 0, v[74:75]
	global_load_lds_dwordx4 v[8:9], off
	v_lshl_add_u64 v[8:9], s[0:1], 0, v[78:79]
	s_mov_b32 m0, s57
	s_nop 0
	global_load_lds_dwordx4 v[8:9], off
	s_waitcnt vmcnt(6)
	s_barrier
	s_setprio 1
	s_setprio 0
	s_add_i32 s79, s79, 2
	s_add_u32 s71, s71, 0x100
	s_addc_u32 s78, s78, 0
	s_add_u32 s34, s34, 0x1800
	s_addc_u32 s35, s35, 0
	s_cmp_gt_u32 s79, 13
	s_barrier
	s_cbranch_scc1 .LBB0_875
.LBB0_871:
	s_cmp_eq_u32 s79, 12
	s_cselect_b64 s[0:1], -1, 0
	s_and_b64 vcc, exec, s[0:1]
	s_mov_b64 s[36:37], s[22:23]
	s_cbranch_vccnz .LBB0_870
	s_add_u32 s36, s34, 0x1800
	s_addc_u32 s37, s35, 0
	s_branch .LBB0_870

.LBB0_875:
	s_cmp_eq_u32 s101, 0
	s_cbranch_scc1 .Lck_recv
	s_cmpk_gt_u32 s38, 0xff
	s_cbranch_scc1 .Lck_aligned
	s_barrier
.Lck_aligned:
	v_readlane_b32 s0, v235, 29
	v_readlane_b32 s1, v235, 30
	s_lshl_b32 s98, s33, 17
	s_add_u32 s0, s0, s98
	s_addc_u32 s1, s1, 0
	s_add_u32 s0, s0, 0x29800000
	s_addc_u32 s1, s1, 0
	v_lshlrev_b32_e32 v8, 4, v188
	global_store_dwordx4 v8, v[0:3], s[0:1]
	s_add_u32 s0, s0, 0x2000
	s_addc_u32 s1, s1, 0
	global_store_dwordx4 v8, v[4:7], s[0:1]
	s_add_u32 s0, s0, 0x2000
	s_addc_u32 s1, s1, 0
	global_store_dwordx4 v8, v[12:15], s[0:1]
	s_add_u32 s0, s0, 0x2000
	s_addc_u32 s1, s1, 0
	global_store_dwordx4 v8, v[20:23], s[0:1]
	s_add_u32 s0, s0, 0x2000
	s_addc_u32 s1, s1, 0
	global_store_dwordx4 v8, v[24:27], s[0:1]
	s_add_u32 s0, s0, 0x2000
	s_addc_u32 s1, s1, 0
	global_store_dwordx4 v8, v[28:31], s[0:1]
	s_add_u32 s0, s0, 0x2000
	s_addc_u32 s1, s1, 0
	global_store_dwordx4 v8, v[32:35], s[0:1]
	s_add_u32 s0, s0, 0x2000
	s_addc_u32 s1, s1, 0
	global_store_dwordx4 v8, v[36:39], s[0:1]
	s_add_u32 s0, s0, 0x2000
	s_addc_u32 s1, s1, 0
	global_store_dwordx4 v8, v[40:43], s[0:1]
	s_add_u32 s0, s0, 0x2000
	s_addc_u32 s1, s1, 0
	global_store_dwordx4 v8, v[44:47], s[0:1]
	s_add_u32 s0, s0, 0x2000
	s_addc_u32 s1, s1, 0
	global_store_dwordx4 v8, v[48:51], s[0:1]
	s_add_u32 s0, s0, 0x2000
	s_addc_u32 s1, s1, 0
	global_store_dwordx4 v8, v[52:55], s[0:1]
	s_add_u32 s0, s0, 0x2000
	s_addc_u32 s1, s1, 0
	global_store_dwordx4 v8, v[56:59], s[0:1]
	s_add_u32 s0, s0, 0x2000
	s_addc_u32 s1, s1, 0
	global_store_dwordx4 v8, v[60:63], s[0:1]
	s_add_u32 s0, s0, 0x2000
	s_addc_u32 s1, s1, 0
	global_store_dwordx4 v8, v[64:67], s[0:1]
	s_add_u32 s0, s0, 0x2000
	s_addc_u32 s1, s1, 0
	global_store_dwordx4 v8, v[68:71], s[0:1]
	s_waitcnt vmcnt(0)
	buffer_wbl2 sc1
	s_waitcnt vmcnt(0)
	s_barrier
	s_and_saveexec_b64 s[98:99], s[96:97]
	s_cbranch_execz .Lck_sigdone
	v_readlane_b32 s0, v235, 29
	v_readlane_b32 s1, v235, 30
	s_lshl_b32 vcc_lo, s33, 2
	s_add_u32 s0, s0, vcc_lo
	s_addc_u32 s1, s1, 0
	s_add_u32 s0, s0, 0x37443800
	s_addc_u32 s1, s1, 0
	v_mov_b32_e32 v8, 0
	v_mov_b32_e32 v9, 1
	global_atomic_add v8, v9, s[0:1]
	s_waitcnt vmcnt(0)
.Lck_sigdone:
	s_or_b64 exec, exec, s[98:99]
	s_branch .LBB0_1133
.Lck_recv:
	v_readlane_b32 s0, v235, 29
	v_readlane_b32 s1, v235, 30
	s_lshl_b32 s98, s33, 2
	s_add_u32 s98, s0, s98
	s_addc_u32 s99, s1, 0
	s_add_u32 s98, s98, 0x37443800
	s_addc_u32 s99, s99, 0
	v_mov_b32_e32 v8, 0
	s_mov_b32 s0, 0
.Lck_spin:
	global_load_dword v9, v8, s[98:99] sc1
	s_waitcnt vmcnt(0)
	v_readfirstlane_b32 s1, v9
	s_cmp_lg_u32 s1, 0
	s_cbranch_scc1 .Lck_got
	s_sleep 1
	s_add_i32 s0, s0, 1
	s_cmp_lt_u32 s0, 0x10000
	s_cbranch_scc1 .Lck_spin
.Lck_got:
	buffer_inv sc1
	v_readlane_b32 s0, v235, 29
	v_readlane_b32 s1, v235, 30
	s_lshl_b32 s98, s33, 17
	s_add_u32 s0, s0, s98
	s_addc_u32 s1, s1, 0
	s_add_u32 s0, s0, 0x29800000
	s_addc_u32 s1, s1, 0
	v_lshlrev_b32_e32 v8, 4, v188
	global_load_dwordx4 v[98:101], v8, s[0:1]
	s_add_u32 s0, s0, 0x2000
	s_addc_u32 s1, s1, 0
	global_load_dwordx4 v[102:105], v8, s[0:1]
	s_add_u32 s0, s0, 0x2000
	s_addc_u32 s1, s1, 0
	global_load_dwordx4 v[106:109], v8, s[0:1]
	s_add_u32 s0, s0, 0x2000
	s_addc_u32 s1, s1, 0
	global_load_dwordx4 v[110:113], v8, s[0:1]
	s_add_u32 s0, s0, 0x2000
	s_addc_u32 s1, s1, 0
	global_load_dwordx4 v[114:117], v8, s[0:1]
	s_add_u32 s0, s0, 0x2000
	s_addc_u32 s1, s1, 0
	global_load_dwordx4 v[118:121], v8, s[0:1]
	s_add_u32 s0, s0, 0x2000
	s_addc_u32 s1, s1, 0
	global_load_dwordx4 v[122:125], v8, s[0:1]
	s_add_u32 s0, s0, 0x2000
	s_addc_u32 s1, s1, 0
	global_load_dwordx4 v[126:129], v8, s[0:1]
	s_add_u32 s0, s0, 0x2000
	s_addc_u32 s1, s1, 0
	s_waitcnt vmcnt(0)
	v_add_f32_e32 v0, v0, v98
	v_add_f32_e32 v1, v1, v99
	v_add_f32_e32 v2, v2, v100
	v_add_f32_e32 v3, v3, v101
	v_add_f32_e32 v4, v4, v102
	v_add_f32_e32 v5, v5, v103
	v_add_f32_e32 v6, v6, v104
	v_add_f32_e32 v7, v7, v105
	v_add_f32_e32 v12, v12, v106
	v_add_f32_e32 v13, v13, v107
	v_add_f32_e32 v14, v14, v108
	v_add_f32_e32 v15, v15, v109
	v_add_f32_e32 v20, v20, v110
	v_add_f32_e32 v21, v21, v111
	v_add_f32_e32 v22, v22, v112
	v_add_f32_e32 v23, v23, v113
	v_add_f32_e32 v24, v24, v114
	v_add_f32_e32 v25, v25, v115
	v_add_f32_e32 v26, v26, v116
	v_add_f32_e32 v27, v27, v117
	v_add_f32_e32 v28, v28, v118
	v_add_f32_e32 v29, v29, v119
	v_add_f32_e32 v30, v30, v120
	v_add_f32_e32 v31, v31, v121
	v_add_f32_e32 v32, v32, v122
	v_add_f32_e32 v33, v33, v123
	v_add_f32_e32 v34, v34, v124
	v_add_f32_e32 v35, v35, v125
	v_add_f32_e32 v36, v36, v126
	v_add_f32_e32 v37, v37, v127
	v_add_f32_e32 v38, v38, v128
	v_add_f32_e32 v39, v39, v129
	global_load_dwordx4 v[98:101], v8, s[0:1]
	s_add_u32 s0, s0, 0x2000
	s_addc_u32 s1, s1, 0
	global_load_dwordx4 v[102:105], v8, s[0:1]
	s_add_u32 s0, s0, 0x2000
	s_addc_u32 s1, s1, 0
	global_load_dwordx4 v[106:109], v8, s[0:1]
	s_add_u32 s0, s0, 0x2000
	s_addc_u32 s1, s1, 0
	global_load_dwordx4 v[110:113], v8, s[0:1]
	s_add_u32 s0, s0, 0x2000
	s_addc_u32 s1, s1, 0
	global_load_dwordx4 v[114:117], v8, s[0:1]
	s_add_u32 s0, s0, 0x2000
	s_addc_u32 s1, s1, 0
	global_load_dwordx4 v[118:121], v8, s[0:1]
	s_add_u32 s0, s0, 0x2000
	s_addc_u32 s1, s1, 0
	global_load_dwordx4 v[122:125], v8, s[0:1]
	s_add_u32 s0, s0, 0x2000
	s_addc_u32 s1, s1, 0
	global_load_dwordx4 v[126:129], v8, s[0:1]
	s_waitcnt vmcnt(0)
	v_add_f32_e32 v40, v40, v98
	v_add_f32_e32 v41, v41, v99
	v_add_f32_e32 v42, v42, v100
	v_add_f32_e32 v43, v43, v101
	v_add_f32_e32 v44, v44, v102
	v_add_f32_e32 v45, v45, v103
	v_add_f32_e32 v46, v46, v104
	v_add_f32_e32 v47, v47, v105
	v_add_f32_e32 v48, v48, v106
	v_add_f32_e32 v49, v49, v107
	v_add_f32_e32 v50, v50, v108
	v_add_f32_e32 v51, v51, v109
	v_add_f32_e32 v52, v52, v110
	v_add_f32_e32 v53, v53, v111
	v_add_f32_e32 v54, v54, v112
	v_add_f32_e32 v55, v55, v113
	v_add_f32_e32 v56, v56, v114
	v_add_f32_e32 v57, v57, v115
	v_add_f32_e32 v58, v58, v116
	v_add_f32_e32 v59, v59, v117
	v_add_f32_e32 v60, v60, v118
	v_add_f32_e32 v61, v61, v119
	v_add_f32_e32 v62, v62, v120
	v_add_f32_e32 v63, v63, v121
	v_add_f32_e32 v64, v64, v122
	v_add_f32_e32 v65, v65, v123
	v_add_f32_e32 v66, v66, v124
	v_add_f32_e32 v67, v67, v125
	v_add_f32_e32 v68, v68, v126
	v_add_f32_e32 v69, v69, v127
	v_add_f32_e32 v70, v70, v128
	v_add_f32_e32 v71, v71, v129
	s_lshl_b32 s0, s30, 7
	s_ashr_i32 s1, s0, 31
	v_lshl_add_u64 v[8:9], s[0:1], 2, v[84:85]
	global_load_dwordx4 v[16:19], v[8:9], off
	s_nop 0
	global_load_dwordx4 v[8:11], v[8:9], off offset:16
	s_waitcnt vmcnt(0)
	v_pk_add_f32 v[68:69], v[68:69], v[16:17]
	s_nop 0
	v_mul_f32_e32 v80, 0x3d372713, v68
	v_mul_f32_e32 v80, v68, v80
	v_fma_f32 v80, v68, v80, v68
	v_mul_f32_e32 v80, 0x3f4c422a, v80
	v_cmp_nlt_f32_e64 s[0:1], |v80|, s61
	s_and_saveexec_b64 s[34:35], s[0:1]
	s_xor_b64 s[0:1], exec, s[34:35]
	s_cbranch_execz .LBB0_877
	v_add_f32_e64 v98, |v80|, |v80|
	v_mul_f32_e32 v99, 0x3fb8aa3b, v98
	v_rndne_f32_e32 v100, v99
	v_sub_f32_e32 v101, v99, v100
	v_fma_f32 v99, v98, s62, -v99
	v_fmac_f32_e32 v99, 0x32a5705f, v98
	v_add_f32_e32 v99, v101, v99
	v_cvt_i32_f32_e32 v100, v100
	v_exp_f32_e32 v99, v99
	v_cmp_ngt_f32_e32 vcc, s63, v98
	v_ldexp_f32 v99, v99, v100
	s_nop 0
	v_cndmask_b32_e32 v99, 0, v99, vcc
	v_cmp_nlt_f32_e32 vcc, s67, v98
	s_nop 1
	v_cndmask_b32_e32 v98, v97, v99, vcc
	v_add_f32_e32 v98, 1.0, v98
	v_rcp_f32_e32 v98, v98
	s_nop 0
	v_fma_f32 v98, v98, -2.0, 1.0

.LBB0_1134:
	s_mov_b32 s33, s100
	s_cmp_gt_i32 s47, 9
	s_cselect_b64 s[0:1], -1, 0
	s_and_b64 s[2:3], s[4:5], s[0:1]
	s_andn2_b64 vcc, exec, s[2:3]
	s_cbranch_vccnz .LBB0_1188
	s_waitcnt vmcnt(0)
	s_waitcnt vmcnt(0) lgkmcnt(0)
	s_barrier
	s_and_saveexec_b64 s[2:3], s[96:97]
	s_cbranch_execz .LBB0_1187
	s_add_i32 s4, 0, 0x24000
	v_mov_b32_e32 v0, s4
	s_waitcnt vmcnt(0) expcnt(0) lgkmcnt(0)
	ds_read_b32 v2, v0
	s_add_i32 s4, 0, 0x24004
	v_mov_b32_e32 v0, s4
	ds_read_b32 v0, v0
	s_waitcnt lgkmcnt(1)
	v_cmp_ne_u32_e32 vcc, 0, v2
	s_cbranch_vccnz .LBB0_1151
	v_readlane_b32 s4, v235, 0
	v_readlane_b32 s5, v235, 1
	s_load_dwordx2 s[8:9], s[4:5], 0x4
	s_add_u32 s4, s44, 0x37440200
	s_addc_u32 s5, s45, 0
	s_add_u32 s6, s44, 0x37440400
	s_addc_u32 s7, s45, 0
	s_waitcnt lgkmcnt(0)
	s_mul_i32 s52, s8, s66
	s_add_u32 s8, s44, 0x37440500
	s_mul_i32 s52, s52, s9
	s_addc_u32 s9, s45, 0
	s_add_u32 s10, s44, 0x37440600
	s_addc_u32 s11, s45, 0
	s_add_u32 s12, s44, 0x37440700
	s_addc_u32 s13, s45, 0
	s_add_u32 s14, s44, 0x37440800
	s_addc_u32 s15, s45, 0
	s_add_u32 s18, s44, 0x37440900
	s_addc_u32 s19, s45, 0
	s_add_u32 s20, s44, 0x37440a00
	s_addc_u32 s21, s45, 0
	s_add_u32 s22, s44, 0x37440b00
	s_addc_u32 s23, s45, 0
	s_add_u32 s28, s44, 0x37440c00
	s_addc_u32 s29, s45, 0
	s_add_u32 s30, s44, 0x37440d00
	s_addc_u32 s31, s45, 0
	s_add_u32 s34, s44, 0x37440e00
	s_addc_u32 s35, s45, 0
	s_add_u32 s36, s44, 0x37440f00
	s_addc_u32 s37, s45, 0
	s_add_u32 s38, s44, 0x37441000
	s_addc_u32 s39, s45, 0
	s_add_u32 s40, s44, 0x37441100
	s_addc_u32 s41, s45, 0
	s_add_u32 s42, s44, 0x37441200
	s_addc_u32 s43, s45, 0
	s_add_u32 s44, s44, 0x37441300
	s_addc_u32 s45, s45, 0
	s_mov_b32 s53, 1
	v_mov_b32_e32 v16, 0
	s_branch .LBB0_1139
